# F5 gate carry + F2 epilogue counted waits + K-loop trim
# baseline (speedup 1.0000x reference)
.LBB0_440:
	v_lshl_or_b32 v178, s79, 8, v198
	v_lshl_add_u32 v180, s78, 8, v196
	v_ashrrev_i32_e32 v179, 31, v178
	v_lshlrev_b64 v[204:205], 1, v[178:179]
	v_ashrrev_i32_e32 v181, 31, v180
	v_lshl_add_u64 v[182:183], s[10:11], 0, v[204:205]
	v_lshlrev_b64 v[206:207], 12, v[180:181]
	v_lshl_add_u64 v[114:115], v[182:183], 0, v[206:207]
	global_load_dwordx4 v[200:203], v[114:115], off
	global_load_dwordx4 v[154:157], v[114:115], off offset:256
	v_or_b32_e32 v194, 16, v180
	v_ashrrev_i32_e32 v195, 31, v194
	v_or_b32_e32 v190, 32, v180
	v_lshlrev_b64 v[192:193], 12, v[194:195]
	v_ashrrev_i32_e32 v191, 31, v190
	v_or_b32_e32 v186, 48, v180
	v_lshl_add_u64 v[114:115], v[182:183], 0, v[192:193]
	v_lshlrev_b64 v[188:189], 12, v[190:191]
	v_ashrrev_i32_e32 v187, 31, v186
	global_load_dwordx4 v[142:145], v[114:115], off
	global_load_dwordx4 v[138:141], v[114:115], off offset:256
	v_lshl_add_u64 v[114:115], v[182:183], 0, v[188:189]
	v_lshlrev_b64 v[184:185], 12, v[186:187]
	global_load_dwordx4 v[126:129], v[114:115], off
	global_load_dwordx4 v[122:125], v[114:115], off offset:256
	v_lshl_add_u64 v[114:115], v[182:183], 0, v[184:185]
	global_load_dwordx4 v[118:121], v[114:115], off
	s_nop 0
	global_load_dwordx4 v[114:117], v[114:115], off offset:256
	v_lshlrev_b64 v[208:209], 11, v[180:181]
	v_lshl_add_u64 v[208:209], v[208:209], 0, v[178:179]
	s_waitcnt vmcnt(7)
	v_cvt_f32_f16_e32 v210, v200
	v_cvt_f32_f16_sdwa v211, v200 dst_sel:DWORD dst_unused:UNUSED_PAD src0_sel:WORD_1
	v_cvt_f32_f16_e32 v200, v201
	v_cvt_f32_f16_sdwa v201, v201 dst_sel:DWORD dst_unused:UNUSED_PAD src0_sel:WORD_1
	v_pk_fma_f32 v[210:211], v[150:151], 0.5, v[210:211] op_sel_hi:[1,0,1]
	s_nop 0
	v_cvt_pk_f16_f32 v150, v210, v211
	v_pk_fma_f32 v[200:201], v[152:153], 0.5, v[200:201] op_sel_hi:[1,0,1]
	v_cvt_f32_f16_e32 v152, v202
	v_cvt_f32_f16_sdwa v153, v202 dst_sel:DWORD dst_unused:UNUSED_PAD src0_sel:WORD_1
	v_cvt_pk_f16_f32 v151, v200, v201
	v_pk_fma_f32 v[212:213], v[146:147], 0.5, v[152:153] op_sel_hi:[1,0,1]
	v_cvt_f32_f16_e32 v146, v203
	v_cvt_f32_f16_sdwa v147, v203 dst_sel:DWORD dst_unused:UNUSED_PAD src0_sel:WORD_1
	v_cvt_pk_f16_f32 v152, v212, v213
	v_pk_fma_f32 v[202:203], v[148:149], 0.5, v[146:147] op_sel_hi:[1,0,1]
	v_lshl_add_u64 v[146:147], s[12:13], 0, v[206:207]
	v_lshl_add_u64 v[204:205], v[146:147], 0, v[204:205]
	v_mov_b32_e32 v146, 0
	v_dot2c_f32_f16_e32 v146, v150, v150
	v_dot2c_f32_f16_e32 v146, v151, v151
	v_cvt_pk_f16_f32 v153, v202, v203
	v_dot2c_f32_f16_e32 v146, v152, v152
	global_store_dwordx4 v[204:205], v[150:153], off
	v_dot2c_f32_f16_e32 v146, v153, v153
	s_nop 0
	v_lshlrev_b64 v[150:151], 1, v[208:209]
	v_lshl_add_u64 v[152:153], s[16:17], 0, v[150:151]
	v_add_f32_e32 v168, 0, v146
	v_cvt_pk_bf16_f32 v146, v210, v211
	v_cvt_pk_bf16_f32 v147, v200, v201
	v_cvt_pk_bf16_f32 v148, v212, v213
	v_cvt_pk_bf16_f32 v149, v202, v203
	global_store_dwordx4 v[152:153], v[146:149], off
	v_or_b32_e32 v150, 0x100, v150
	s_nop 0
	s_waitcnt vmcnt(8)
	v_cvt_f32_f16_e32 v148, v155
	v_cvt_f32_f16_sdwa v149, v155 dst_sel:DWORD dst_unused:UNUSED_PAD src0_sel:WORD_1
	v_cvt_f32_f16_e32 v146, v154
	v_cvt_f32_f16_sdwa v147, v154 dst_sel:DWORD dst_unused:UNUSED_PAD src0_sel:WORD_1
	v_pk_fma_f32 v[148:149], v[136:137], 0.5, v[148:149] op_sel_hi:[1,0,1]
	v_cvt_f32_f16_e32 v136, v156
	v_cvt_f32_f16_sdwa v137, v156 dst_sel:DWORD dst_unused:UNUSED_PAD src0_sel:WORD_1
	v_pk_fma_f32 v[146:147], v[134:135], 0.5, v[146:147] op_sel_hi:[1,0,1]
	v_cvt_pk_f16_f32 v135, v148, v149
	v_cvt_pk_f16_f32 v134, v146, v147
	v_pk_fma_f32 v[152:153], v[130:131], 0.5, v[136:137] op_sel_hi:[1,0,1]
	v_cvt_f32_f16_e32 v130, v157
	v_cvt_f32_f16_sdwa v131, v157 dst_sel:DWORD dst_unused:UNUSED_PAD src0_sel:WORD_1
	v_cvt_pk_f16_f32 v136, v152, v153
	v_pk_fma_f32 v[154:155], v[132:133], 0.5, v[130:131] op_sel_hi:[1,0,1]
	v_mov_b32_e32 v130, 0
	v_dot2c_f32_f16_e32 v130, v134, v134
	v_dot2c_f32_f16_e32 v130, v135, v135
	v_cvt_pk_f16_f32 v137, v154, v155
	v_dot2c_f32_f16_e32 v130, v136, v136
	v_dot2c_f32_f16_e32 v130, v137, v137
	global_store_dwordx4 v[204:205], v[134:137], off offset:256
	s_nop 1
	v_add_f32_e32 v136, v168, v130
	v_cvt_pk_bf16_f32 v130, v146, v147
	v_cvt_pk_bf16_f32 v131, v148, v149
	v_lshl_add_u64 v[134:135], s[16:17], 0, v[150:151]
	v_cvt_pk_bf16_f32 v132, v152, v153
	v_cvt_pk_bf16_f32 v133, v154, v155
	global_store_dwordx4 v[134:135], v[130:133], off
	s_nop 1
	v_and_b32_e32 v131, 64, v218
	v_xor_b32_e32 v130, 16, v218
	v_add_u32_e32 v131, 64, v131
	v_cmp_lt_i32_e32 vcc, v130, v131
	s_nop 1
	v_cndmask_b32_e32 v130, v218, v130, vcc
	v_lshlrev_b32_e32 v146, 2, v130
	ds_bpermute_b32 v130, v146, v136
	s_waitcnt lgkmcnt(0)
	v_add_f32_e32 v132, v136, v130
	v_xor_b32_e32 v130, 32, v218
	v_cmp_lt_i32_e32 vcc, v130, v131
	s_nop 1
	v_cndmask_b32_e32 v130, v218, v130, vcc
	v_lshlrev_b32_e32 v147, 2, v130
	ds_bpermute_b32 v133, v147, v132
	v_lshl_add_u64 v[130:131], v[180:181], 3, s[14:15]
	s_and_saveexec_b64 s[24:25], s[4:5]
	s_cbranch_execz .LBB0_442
	s_waitcnt lgkmcnt(0)
	v_add_f32_e32 v132, v132, v133
	v_fma_f32 v132, v132, s33, 0.5
	v_trunc_f32_e32 v132, v132
	v_mul_f32_e32 v133, 0x2f800000, v132
	v_floor_f32_e32 v133, v133
	v_fmac_f32_e32 v132, 0xcf800000, v133
	v_cvt_u32_f32_e32 v132, v132
	v_cvt_u32_f32_e32 v133, v133
	global_atomic_add_x2 v[130:131], v[132:133], off
.LBB0_442:
	s_or_b64 exec, exec, s[24:25]
	s_waitcnt vmcnt(9)
	v_cvt_f32_f16_sdwa v137, v143 dst_sel:DWORD dst_unused:UNUSED_PAD src0_sel:WORD_1
	v_cvt_f32_f16_e32 v136, v143
	v_cvt_f32_f16_sdwa v135, v142 dst_sel:DWORD dst_unused:UNUSED_PAD src0_sel:WORD_1
	v_cvt_f32_f16_e32 v134, v142
	s_waitcnt lgkmcnt(0)
	v_lshlrev_b64 v[132:133], 11, v[194:195]
	v_pk_fma_f32 v[136:137], v[112:113], 0.5, v[136:137] op_sel_hi:[1,0,1]
	v_cvt_f32_f16_sdwa v113, v144 dst_sel:DWORD dst_unused:UNUSED_PAD src0_sel:WORD_1
	v_cvt_f32_f16_e32 v112, v144
	v_pk_fma_f32 v[134:135], v[110:111], 0.5, v[134:135] op_sel_hi:[1,0,1]
	v_cvt_pk_f16_f32 v111, v136, v137
	v_cvt_pk_f16_f32 v110, v134, v135
	v_pk_fma_f32 v[142:143], v[106:107], 0.5, v[112:113] op_sel_hi:[1,0,1]
	v_cvt_f32_f16_sdwa v107, v145 dst_sel:DWORD dst_unused:UNUSED_PAD src0_sel:WORD_1
	v_cvt_f32_f16_e32 v106, v145
	v_cvt_pk_f16_f32 v112, v142, v143
	v_lshl_add_u64 v[132:133], v[132:133], 0, v[178:179]
	v_pk_fma_f32 v[144:145], v[108:109], 0.5, v[106:107] op_sel_hi:[1,0,1]
	v_lshl_add_u64 v[106:107], s[12:13], 0, v[192:193]
	v_lshl_add_u64 v[148:149], v[178:179], 1, v[106:107]
	v_mov_b32_e32 v106, 0
	v_dot2c_f32_f16_e32 v106, v110, v110
	v_dot2c_f32_f16_e32 v106, v111, v111
	v_cvt_pk_f16_f32 v113, v144, v145
	v_dot2c_f32_f16_e32 v106, v112, v112
	global_store_dwordx4 v[148:149], v[110:113], off
	v_dot2c_f32_f16_e32 v106, v113, v113
	s_nop 0
	v_lshlrev_b64 v[110:111], 1, v[132:133]
	v_lshl_add_u64 v[112:113], s[16:17], 0, v[110:111]
	v_add_f32_e32 v150, 0, v106
	v_cvt_pk_bf16_f32 v106, v134, v135
	v_cvt_pk_bf16_f32 v107, v136, v137
	v_cvt_pk_bf16_f32 v108, v142, v143
	v_cvt_pk_bf16_f32 v109, v144, v145
	global_store_dwordx4 v[112:113], v[106:109], off
	v_or_b32_e32 v110, 0x100, v110
	s_nop 0
	s_waitcnt vmcnt(10)
	v_cvt_f32_f16_sdwa v109, v139 dst_sel:DWORD dst_unused:UNUSED_PAD src0_sel:WORD_1
	v_cvt_f32_f16_e32 v108, v139
	v_cvt_f32_f16_sdwa v107, v138 dst_sel:DWORD dst_unused:UNUSED_PAD src0_sel:WORD_1
	v_cvt_f32_f16_e32 v106, v138
	v_pk_fma_f32 v[108:109], v[104:105], 0.5, v[108:109] op_sel_hi:[1,0,1]
	v_cvt_f32_f16_sdwa v105, v140 dst_sel:DWORD dst_unused:UNUSED_PAD src0_sel:WORD_1
	v_cvt_f32_f16_e32 v104, v140
	v_pk_fma_f32 v[106:107], v[102:103], 0.5, v[106:107] op_sel_hi:[1,0,1]
	v_cvt_pk_f16_f32 v103, v108, v109
	v_cvt_pk_f16_f32 v102, v106, v107
	v_pk_fma_f32 v[112:113], v[98:99], 0.5, v[104:105] op_sel_hi:[1,0,1]
	v_cvt_f32_f16_sdwa v99, v141 dst_sel:DWORD dst_unused:UNUSED_PAD src0_sel:WORD_1
	v_cvt_f32_f16_e32 v98, v141
	v_cvt_pk_f16_f32 v104, v112, v113
	v_pk_fma_f32 v[132:133], v[100:101], 0.5, v[98:99] op_sel_hi:[1,0,1]
	v_mov_b32_e32 v98, 0
	v_dot2c_f32_f16_e32 v98, v102, v102
	v_dot2c_f32_f16_e32 v98, v103, v103
	v_cvt_pk_f16_f32 v105, v132, v133
	v_dot2c_f32_f16_e32 v98, v104, v104
	v_dot2c_f32_f16_e32 v98, v105, v105
	global_store_dwordx4 v[148:149], v[102:105], off offset:256
	s_nop 1
	v_add_f32_e32 v104, v150, v98
	v_cvt_pk_bf16_f32 v98, v106, v107
	v_lshl_add_u64 v[102:103], s[16:17], 0, v[110:111]
	v_cvt_pk_bf16_f32 v99, v108, v109
	v_cvt_pk_bf16_f32 v100, v112, v113
	v_cvt_pk_bf16_f32 v101, v132, v133
	global_store_dwordx4 v[102:103], v[98:101], off
	ds_bpermute_b32 v98, v146, v104
	s_waitcnt lgkmcnt(0)
	v_add_f32_e32 v98, v104, v98
	ds_bpermute_b32 v99, v147, v98
	s_and_saveexec_b64 s[24:25], s[4:5]
	s_cbranch_execz .LBB0_444
	s_waitcnt lgkmcnt(0)
	v_add_f32_e32 v98, v98, v99
	v_fma_f32 v98, v98, s33, 0.5
	v_trunc_f32_e32 v98, v98
	v_mul_f32_e32 v99, 0x2f800000, v98
	v_floor_f32_e32 v99, v99
	v_fmac_f32_e32 v98, 0xcf800000, v99
	v_cvt_u32_f32_e32 v98, v98
	v_cvt_u32_f32_e32 v99, v99
	global_atomic_add_x2 v[130:131], v[98:99], off offset:128
.LBB0_444:
	s_or_b64 exec, exec, s[24:25]
	v_add_u32_e32 v138, 0x80, v180
	v_ashrrev_i32_e32 v139, 31, v138
	v_add_u32_e32 v134, 0x90, v180
	v_lshlrev_b64 v[136:137], 12, v[138:139]
	v_ashrrev_i32_e32 v135, 31, v134
	s_waitcnt lgkmcnt(0)
	v_lshl_add_u64 v[98:99], v[182:183], 0, v[136:137]
	v_lshlrev_b64 v[132:133], 12, v[134:135]
	global_load_dwordx4 v[110:113], v[98:99], off
	global_load_dwordx4 v[106:109], v[98:99], off offset:256
	v_lshl_add_u64 v[98:99], v[182:183], 0, v[132:133]
	global_load_dwordx4 v[102:105], v[98:99], off
	s_nop 0
	global_load_dwordx4 v[98:101], v[98:99], off offset:256
	s_waitcnt vmcnt(15)
	v_cvt_f32_f16_sdwa v145, v127 dst_sel:DWORD dst_unused:UNUSED_PAD src0_sel:WORD_1
	v_cvt_f32_f16_e32 v144, v127
	v_cvt_f32_f16_sdwa v143, v126 dst_sel:DWORD dst_unused:UNUSED_PAD src0_sel:WORD_1
	v_cvt_f32_f16_e32 v142, v126
	v_lshlrev_b64 v[140:141], 11, v[190:191]
	v_pk_fma_f32 v[126:127], v[96:97], 0.5, v[144:145] op_sel_hi:[1,0,1]
	v_cvt_f32_f16_sdwa v97, v128 dst_sel:DWORD dst_unused:UNUSED_PAD src0_sel:WORD_1
	v_cvt_f32_f16_e32 v96, v128
	v_pk_fma_f32 v[142:143], v[94:95], 0.5, v[142:143] op_sel_hi:[1,0,1]
	v_cvt_pk_f16_f32 v95, v126, v127
	v_cvt_pk_f16_f32 v94, v142, v143
	v_pk_fma_f32 v[144:145], v[90:91], 0.5, v[96:97] op_sel_hi:[1,0,1]
	v_cvt_f32_f16_sdwa v91, v129 dst_sel:DWORD dst_unused:UNUSED_PAD src0_sel:WORD_1
	v_cvt_f32_f16_e32 v90, v129
	v_cvt_pk_f16_f32 v96, v144, v145
	v_lshl_add_u64 v[140:141], v[140:141], 0, v[178:179]
	v_pk_fma_f32 v[128:129], v[92:93], 0.5, v[90:91] op_sel_hi:[1,0,1]
	v_lshl_add_u64 v[90:91], s[12:13], 0, v[188:189]
	v_lshl_add_u64 v[148:149], v[178:179], 1, v[90:91]
	v_mov_b32_e32 v90, 0
	v_dot2c_f32_f16_e32 v90, v94, v94
	v_dot2c_f32_f16_e32 v90, v95, v95
	v_cvt_pk_f16_f32 v97, v128, v129
	v_dot2c_f32_f16_e32 v90, v96, v96
	global_store_dwordx4 v[148:149], v[94:97], off
	v_dot2c_f32_f16_e32 v90, v97, v97
	s_nop 0
	v_lshlrev_b64 v[94:95], 1, v[140:141]
	v_lshl_add_u64 v[96:97], s[16:17], 0, v[94:95]
	v_add_f32_e32 v150, 0, v90
	v_cvt_pk_bf16_f32 v90, v142, v143
	v_cvt_pk_bf16_f32 v91, v126, v127
	v_cvt_pk_bf16_f32 v92, v144, v145
	v_cvt_pk_bf16_f32 v93, v128, v129
	global_store_dwordx4 v[96:97], v[90:93], off
	v_or_b32_e32 v94, 0x100, v94
	s_nop 0
	s_waitcnt vmcnt(16)
	v_cvt_f32_f16_sdwa v93, v123 dst_sel:DWORD dst_unused:UNUSED_PAD src0_sel:WORD_1
	v_cvt_f32_f16_e32 v92, v123
	v_cvt_f32_f16_sdwa v91, v122 dst_sel:DWORD dst_unused:UNUSED_PAD src0_sel:WORD_1
	v_cvt_f32_f16_e32 v90, v122
	v_pk_fma_f32 v[92:93], v[88:89], 0.5, v[92:93] op_sel_hi:[1,0,1]
	v_cvt_f32_f16_sdwa v89, v124 dst_sel:DWORD dst_unused:UNUSED_PAD src0_sel:WORD_1
	v_cvt_f32_f16_e32 v88, v124
	v_pk_fma_f32 v[90:91], v[86:87], 0.5, v[90:91] op_sel_hi:[1,0,1]
	v_cvt_pk_f16_f32 v87, v92, v93
	v_cvt_pk_f16_f32 v86, v90, v91
	v_pk_fma_f32 v[96:97], v[82:83], 0.5, v[88:89] op_sel_hi:[1,0,1]
	v_cvt_f32_f16_sdwa v83, v125 dst_sel:DWORD dst_unused:UNUSED_PAD src0_sel:WORD_1
	v_cvt_f32_f16_e32 v82, v125
	v_cvt_pk_f16_f32 v88, v96, v97
	v_pk_fma_f32 v[122:123], v[84:85], 0.5, v[82:83] op_sel_hi:[1,0,1]
	v_mov_b32_e32 v82, 0
	v_dot2c_f32_f16_e32 v82, v86, v86
	v_dot2c_f32_f16_e32 v82, v87, v87
	v_cvt_pk_f16_f32 v89, v122, v123
	v_dot2c_f32_f16_e32 v82, v88, v88
	v_dot2c_f32_f16_e32 v82, v89, v89
	global_store_dwordx4 v[148:149], v[86:89], off offset:256
	s_nop 1
	v_add_f32_e32 v88, v150, v82
	v_cvt_pk_bf16_f32 v82, v90, v91
	v_lshl_add_u64 v[86:87], s[16:17], 0, v[94:95]
	v_cvt_pk_bf16_f32 v83, v92, v93
	v_cvt_pk_bf16_f32 v84, v96, v97
	v_cvt_pk_bf16_f32 v85, v122, v123
	global_store_dwordx4 v[86:87], v[82:85], off
	ds_bpermute_b32 v82, v146, v88
	s_waitcnt lgkmcnt(0)
	v_add_f32_e32 v82, v88, v82
	ds_bpermute_b32 v83, v147, v82
	s_and_saveexec_b64 s[24:25], s[4:5]
	s_cbranch_execz .LBB0_446
	s_waitcnt lgkmcnt(0)
	v_add_f32_e32 v82, v82, v83
	v_fma_f32 v82, v82, s33, 0.5
	v_trunc_f32_e32 v82, v82
	v_mul_f32_e32 v83, 0x2f800000, v82
	v_floor_f32_e32 v83, v83
	v_fmac_f32_e32 v82, 0xcf800000, v83
	v_cvt_u32_f32_e32 v82, v82
	v_cvt_u32_f32_e32 v83, v83
	global_atomic_add_x2 v[130:131], v[82:83], off offset:256
.LBB0_446:
	s_or_b64 exec, exec, s[24:25]
	s_waitcnt vmcnt(17)
	v_cvt_f32_f16_sdwa v87, v119 dst_sel:DWORD dst_unused:UNUSED_PAD src0_sel:WORD_1
	v_cvt_f32_f16_e32 v86, v119
	v_cvt_f32_f16_sdwa v85, v118 dst_sel:DWORD dst_unused:UNUSED_PAD src0_sel:WORD_1
	v_cvt_f32_f16_e32 v84, v118
	s_waitcnt lgkmcnt(0)
	v_lshlrev_b64 v[82:83], 11, v[186:187]
	v_pk_fma_f32 v[86:87], v[80:81], 0.5, v[86:87] op_sel_hi:[1,0,1]
	v_cvt_f32_f16_sdwa v81, v120 dst_sel:DWORD dst_unused:UNUSED_PAD src0_sel:WORD_1
	v_cvt_f32_f16_e32 v80, v120
	v_pk_fma_f32 v[84:85], v[78:79], 0.5, v[84:85] op_sel_hi:[1,0,1]
	v_cvt_pk_f16_f32 v79, v86, v87
	v_cvt_pk_f16_f32 v78, v84, v85
	v_pk_fma_f32 v[88:89], v[74:75], 0.5, v[80:81] op_sel_hi:[1,0,1]
	v_cvt_f32_f16_sdwa v75, v121 dst_sel:DWORD dst_unused:UNUSED_PAD src0_sel:WORD_1
	v_cvt_f32_f16_e32 v74, v121
	v_cvt_pk_f16_f32 v80, v88, v89
	v_lshl_add_u64 v[82:83], v[82:83], 0, v[178:179]
	v_pk_fma_f32 v[90:91], v[76:77], 0.5, v[74:75] op_sel_hi:[1,0,1]
	v_lshl_add_u64 v[74:75], s[12:13], 0, v[184:185]
	v_lshl_add_u64 v[92:93], v[178:179], 1, v[74:75]
	v_mov_b32_e32 v74, 0
	v_dot2c_f32_f16_e32 v74, v78, v78
	v_dot2c_f32_f16_e32 v74, v79, v79
	v_cvt_pk_f16_f32 v81, v90, v91
	v_dot2c_f32_f16_e32 v74, v80, v80
	global_store_dwordx4 v[92:93], v[78:81], off
	v_dot2c_f32_f16_e32 v74, v81, v81
	s_nop 0
	v_lshlrev_b64 v[78:79], 1, v[82:83]
	v_lshl_add_u64 v[80:81], s[16:17], 0, v[78:79]
	v_add_f32_e32 v94, 0, v74
	v_cvt_pk_bf16_f32 v74, v84, v85
	v_cvt_pk_bf16_f32 v75, v86, v87
	v_cvt_pk_bf16_f32 v76, v88, v89
	v_cvt_pk_bf16_f32 v77, v90, v91
	global_store_dwordx4 v[80:81], v[74:77], off
	v_or_b32_e32 v78, 0x100, v78
	s_nop 0
	s_waitcnt vmcnt(18)
	v_cvt_f32_f16_sdwa v77, v115 dst_sel:DWORD dst_unused:UNUSED_PAD src0_sel:WORD_1
	v_cvt_f32_f16_e32 v76, v115
	v_cvt_f32_f16_sdwa v75, v114 dst_sel:DWORD dst_unused:UNUSED_PAD src0_sel:WORD_1
	v_cvt_f32_f16_e32 v74, v114
	v_pk_fma_f32 v[76:77], v[72:73], 0.5, v[76:77] op_sel_hi:[1,0,1]
	v_cvt_f32_f16_sdwa v73, v116 dst_sel:DWORD dst_unused:UNUSED_PAD src0_sel:WORD_1
	v_cvt_f32_f16_e32 v72, v116
	v_pk_fma_f32 v[74:75], v[70:71], 0.5, v[74:75] op_sel_hi:[1,0,1]
	v_cvt_pk_f16_f32 v71, v76, v77
	v_cvt_pk_f16_f32 v70, v74, v75
	v_pk_fma_f32 v[80:81], v[66:67], 0.5, v[72:73] op_sel_hi:[1,0,1]
	v_cvt_f32_f16_sdwa v67, v117 dst_sel:DWORD dst_unused:UNUSED_PAD src0_sel:WORD_1
	v_cvt_f32_f16_e32 v66, v117
	v_cvt_pk_f16_f32 v72, v80, v81
	v_pk_fma_f32 v[82:83], v[68:69], 0.5, v[66:67] op_sel_hi:[1,0,1]
	v_mov_b32_e32 v66, 0
	v_dot2c_f32_f16_e32 v66, v70, v70
	v_dot2c_f32_f16_e32 v66, v71, v71
	v_cvt_pk_f16_f32 v73, v82, v83
	v_dot2c_f32_f16_e32 v66, v72, v72
	v_dot2c_f32_f16_e32 v66, v73, v73
	global_store_dwordx4 v[92:93], v[70:73], off offset:256
	s_nop 1
	v_add_f32_e32 v72, v94, v66
	v_cvt_pk_bf16_f32 v66, v74, v75
	v_lshl_add_u64 v[70:71], s[16:17], 0, v[78:79]
	v_cvt_pk_bf16_f32 v67, v76, v77
	v_cvt_pk_bf16_f32 v68, v80, v81
	v_cvt_pk_bf16_f32 v69, v82, v83
	global_store_dwordx4 v[70:71], v[66:69], off
	ds_bpermute_b32 v66, v146, v72
	s_waitcnt lgkmcnt(0)
	v_add_f32_e32 v66, v72, v66
	ds_bpermute_b32 v67, v147, v66
	s_and_saveexec_b64 s[24:25], s[4:5]
	s_cbranch_execz .LBB0_448
	s_waitcnt lgkmcnt(0)
	v_add_f32_e32 v66, v66, v67
	v_fma_f32 v66, v66, s33, 0.5
	v_trunc_f32_e32 v66, v66
	v_mul_f32_e32 v67, 0x2f800000, v66
	v_floor_f32_e32 v67, v67
	v_fmac_f32_e32 v66, 0xcf800000, v67
	v_cvt_u32_f32_e32 v66, v66
	v_cvt_u32_f32_e32 v67, v67
	global_atomic_add_x2 v[130:131], v[66:67], off offset:384
